# A/B items: end-of-item workgroup barrier moved up to right after the last read of the conv tile (conv + sequence-final rows), so the epilogue no longer sits between the two barriers
# baseline (speedup 1.0000x reference)
.LBB0_796:
	s_or_b64 exec, exec, s[2:3]
	s_and_b64 vcc, exec, s[34:35]
	s_mov_b32 s6, s5
	s_cbranch_vccnz .LBB0_846

.LBB0_840:
	s_or_b64 exec, exec, s[10:11]
	s_nop 0
	s_waitcnt lgkmcnt(0)
	s_barrier
	v_lshl_or_b32 v148, v148, 11, v154
	v_add_u32_e32 v123, 0x1000, v148
	v_pk_mul_f32 v[118:119], v[82:83], v[82:83]
	v_pk_add_f32 v[120:121], v[82:83], v[84:85]
	v_pk_mul_f32 v[114:115], v[140:141], v[140:141]
	v_pk_add_f32 v[116:117], v[140:141], v[142:143]
	v_pk_mul_f32 v[110:111], v[132:133], v[132:133]
	v_pk_add_f32 v[112:113], v[132:133], v[134:135]
	v_pk_mul_f32 v[106:107], v[124:125], v[124:125]
	v_pk_add_f32 v[108:109], v[124:125], v[126:127]
	v_pk_fma_f32 v[118:119], v[84:85], v[84:85], v[118:119]
	v_pk_fma_f32 v[114:115], v[142:143], v[142:143], v[114:115]
	v_pk_fma_f32 v[110:111], v[134:135], v[134:135], v[110:111]
	v_pk_fma_f32 v[106:107], v[126:127], v[126:127], v[106:107]
	v_pk_fma_f32 v[118:119], v[86:87], v[86:87], v[118:119]
	v_pk_add_f32 v[120:121], v[120:121], v[86:87]
	v_pk_fma_f32 v[114:115], v[144:145], v[144:145], v[114:115]
	v_pk_add_f32 v[116:117], v[116:117], v[144:145]
	v_pk_fma_f32 v[110:111], v[136:137], v[136:137], v[110:111]
	v_pk_add_f32 v[112:113], v[112:113], v[136:137]
	v_pk_fma_f32 v[106:107], v[128:129], v[128:129], v[106:107]
	v_pk_add_f32 v[108:109], v[108:109], v[128:129]
	v_pk_fma_f32 v[118:119], v[88:89], v[88:89], v[118:119]
	v_pk_add_f32 v[120:121], v[120:121], v[88:89]
	v_pk_fma_f32 v[114:115], v[146:147], v[146:147], v[114:115]
	v_pk_add_f32 v[116:117], v[116:117], v[146:147]
	v_pk_fma_f32 v[110:111], v[138:139], v[138:139], v[110:111]
	v_pk_add_f32 v[112:113], v[112:113], v[138:139]
	v_pk_fma_f32 v[106:107], v[130:131], v[130:131], v[106:107]
	v_pk_add_f32 v[108:109], v[108:109], v[130:131]
	v_add_f32_e32 v118, v118, v119
	v_add_f32_e32 v114, v114, v115
	v_add_f32_e32 v110, v110, v111
	v_add_f32_e32 v106, v106, v107
	v_add_f32_e32 v119, v120, v121
	v_add_f32_e32 v115, v116, v117
	v_add_f32_e32 v111, v112, v113
	v_add_f32_e32 v107, v108, v109
	v_cndmask_b32_e64 v118, 0, v118, s[38:39]
	v_cndmask_b32_e64 v119, 0, v119, s[38:39]
	v_cndmask_b32_e64 v114, 0, v114, s[38:39]
	v_cndmask_b32_e64 v115, 0, v115, s[38:39]
	v_cndmask_b32_e64 v110, 0, v110, s[38:39]
	v_cndmask_b32_e64 v111, 0, v111, s[38:39]
	v_cndmask_b32_e64 v106, 0, v106, s[38:39]
	v_cndmask_b32_e64 v107, 0, v107, s[38:39]
	s_nop 1
	v_add_f32_dpp v118, v118, v118 quad_perm:[1,0,3,2] row_mask:0xf bank_mask:0xf
	v_add_f32_dpp v119, v119, v119 quad_perm:[1,0,3,2] row_mask:0xf bank_mask:0xf
	v_add_f32_dpp v114, v114, v114 quad_perm:[1,0,3,2] row_mask:0xf bank_mask:0xf
	v_add_f32_dpp v115, v115, v115 quad_perm:[1,0,3,2] row_mask:0xf bank_mask:0xf
	v_add_f32_dpp v110, v110, v110 quad_perm:[1,0,3,2] row_mask:0xf bank_mask:0xf
	v_add_f32_dpp v111, v111, v111 quad_perm:[1,0,3,2] row_mask:0xf bank_mask:0xf
	v_add_f32_dpp v106, v106, v106 quad_perm:[1,0,3,2] row_mask:0xf bank_mask:0xf
	v_add_f32_dpp v107, v107, v107 quad_perm:[1,0,3,2] row_mask:0xf bank_mask:0xf
	v_add_f32_dpp v118, v118, v118 quad_perm:[2,3,0,1] row_mask:0xf bank_mask:0xf
	v_add_f32_dpp v119, v119, v119 quad_perm:[2,3,0,1] row_mask:0xf bank_mask:0xf
	v_add_f32_dpp v114, v114, v114 quad_perm:[2,3,0,1] row_mask:0xf bank_mask:0xf
	v_add_f32_dpp v115, v115, v115 quad_perm:[2,3,0,1] row_mask:0xf bank_mask:0xf
	v_add_f32_dpp v110, v110, v110 quad_perm:[2,3,0,1] row_mask:0xf bank_mask:0xf
	v_add_f32_dpp v111, v111, v111 quad_perm:[2,3,0,1] row_mask:0xf bank_mask:0xf
	v_add_f32_dpp v106, v106, v106 quad_perm:[2,3,0,1] row_mask:0xf bank_mask:0xf
	v_add_f32_dpp v107, v107, v107 quad_perm:[2,3,0,1] row_mask:0xf bank_mask:0xf
	v_add_f32_dpp v118, v118, v118 row_half_mirror row_mask:0xf bank_mask:0xf
	v_add_f32_dpp v119, v119, v119 row_half_mirror row_mask:0xf bank_mask:0xf
	v_add_f32_dpp v114, v114, v114 row_half_mirror row_mask:0xf bank_mask:0xf
	v_add_f32_dpp v115, v115, v115 row_half_mirror row_mask:0xf bank_mask:0xf
	v_add_f32_dpp v110, v110, v110 row_half_mirror row_mask:0xf bank_mask:0xf
	v_add_f32_dpp v111, v111, v111 row_half_mirror row_mask:0xf bank_mask:0xf
	v_add_f32_dpp v106, v106, v106 row_half_mirror row_mask:0xf bank_mask:0xf
	v_add_f32_dpp v107, v107, v107 row_half_mirror row_mask:0xf bank_mask:0xf
	v_add_f32_dpp v118, v118, v118 row_mirror row_mask:0xf bank_mask:0xf
	v_add_f32_dpp v119, v119, v119 row_mirror row_mask:0xf bank_mask:0xf
	v_add_f32_dpp v114, v114, v114 row_mirror row_mask:0xf bank_mask:0xf
	v_add_f32_dpp v115, v115, v115 row_mirror row_mask:0xf bank_mask:0xf
	v_add_f32_dpp v110, v110, v110 row_mirror row_mask:0xf bank_mask:0xf
	v_add_f32_dpp v111, v111, v111 row_mirror row_mask:0xf bank_mask:0xf
	v_add_f32_dpp v106, v106, v106 row_mirror row_mask:0xf bank_mask:0xf
	v_add_f32_dpp v107, v107, v107 row_mirror row_mask:0xf bank_mask:0xf
	v_add_f32_dpp v118, v118, v118 row_bcast:15 row_mask:0xa bank_mask:0xf
	v_add_f32_dpp v119, v119, v119 row_bcast:15 row_mask:0xa bank_mask:0xf
	v_add_f32_dpp v114, v114, v114 row_bcast:15 row_mask:0xa bank_mask:0xf
	v_add_f32_dpp v115, v115, v115 row_bcast:15 row_mask:0xa bank_mask:0xf
	v_add_f32_dpp v110, v110, v110 row_bcast:15 row_mask:0xa bank_mask:0xf
	v_add_f32_dpp v111, v111, v111 row_bcast:15 row_mask:0xa bank_mask:0xf
	v_add_f32_dpp v106, v106, v106 row_bcast:15 row_mask:0xa bank_mask:0xf
	v_add_f32_dpp v107, v107, v107 row_bcast:15 row_mask:0xa bank_mask:0xf
	v_add_f32_dpp v118, v118, v118 row_bcast:31 row_mask:0xc bank_mask:0xf
	v_add_f32_dpp v119, v119, v119 row_bcast:31 row_mask:0xc bank_mask:0xf
	v_add_f32_dpp v114, v114, v114 row_bcast:31 row_mask:0xc bank_mask:0xf
	v_add_f32_dpp v115, v115, v115 row_bcast:31 row_mask:0xc bank_mask:0xf
	v_add_f32_dpp v110, v110, v110 row_bcast:31 row_mask:0xc bank_mask:0xf
	v_add_f32_dpp v111, v111, v111 row_bcast:31 row_mask:0xc bank_mask:0xf
	v_add_f32_dpp v106, v106, v106 row_bcast:31 row_mask:0xc bank_mask:0xf
	v_add_f32_dpp v107, v107, v107 row_bcast:31 row_mask:0xc bank_mask:0xf
	s_nop 0
	v_readlane_b32 s2, v118, 63
	v_readlane_b32 s3, v119, 63
	v_readlane_b32 s10, v114, 63
	v_readlane_b32 s11, v115, 63
	v_mov_b32_e32 v120, 0
	v_mov_b32_e32 v121, 0
	v_mov_b32_e32 v116, 0
	v_mov_b32_e32 v117, 0
	v_mov_b32_e32 v118, s2
	v_mov_b32_e32 v119, s3
	v_mov_b32_e32 v114, s10
	v_mov_b32_e32 v115, s11
	s_nop 0
	v_readlane_b32 s2, v110, 63
	v_readlane_b32 s3, v111, 63
	v_readlane_b32 s10, v106, 63
	v_readlane_b32 s11, v107, 63
	v_mov_b32_e32 v112, 0
	v_mov_b32_e32 v113, 0
	v_mov_b32_e32 v108, 0
	v_mov_b32_e32 v109, 0
	v_mov_b32_e32 v110, s2
	v_mov_b32_e32 v111, s3
	v_mov_b32_e32 v106, s10
	v_mov_b32_e32 v107, s11
	s_and_saveexec_b64 s[12:13], s[38:39]
	s_cbranch_execz .LBB0_842
	v_mov_b64_e32 v[90:91], v[194:195]
	v_mov_b64_e32 v[92:93], v[196:197]
	v_mov_b64_e32 v[98:99], v[198:199]
	v_mov_b64_e32 v[100:101], v[200:201]
	v_mov_b64_e32 v[94:95], v[202:203]
	v_mov_b64_e32 v[96:97], v[204:205]
	v_mov_b64_e32 v[102:103], v[206:207]
	v_mov_b64_e32 v[104:105], v[208:209]
	v_pk_add_f32 v[118:119], v[118:119], v[120:121]
	s_mov_b32 s2, 0x3b2aaaab
	v_pk_mul_f32 v[118:119], v[118:119], s[2:3] op_sel_hi:[1,0]
	v_and_b32_e32 v150, 0xffff0000, v81
	v_fma_f32 v118, -v119, v119, v118
	v_max_f32_e32 v118, 0, v118
	v_add_f32_e32 v118, 0x358637bd, v118
	v_cmp_gt_f32_e32 vcc, s33, v118
	v_mul_f32_e32 v120, 0x4b800000, v118
	v_cndmask_b32_e32 v118, v118, v120, vcc
	v_rsq_f32_e32 v118, v118
	s_nop 0
	v_mul_f32_e32 v120, 0x45800000, v118
	v_cndmask_b32_e32 v118, v118, v120, vcc
	v_mul_f32_e64 v248, -v119, v118
	v_fma_f32 v89, v89, v118, v248
	v_fma_f32 v88, v88, v118, v248
	v_fma_f32 v87, v87, v118, v248
	v_lshlrev_b32_e32 v81, 16, v81
	v_fma_f32 v86, v86, v118, v248
	v_fma_f32 v85, v85, v118, v248
	v_fma_f32 v84, v84, v118, v248
	v_fma_f32 v83, v83, v118, v248
	v_fma_f32 v82, v82, v118, v248
	s_mov_b32 s10, s66
	s_mov_b32 s11, s67
	v_fma_f32 v85, v85, v97, v93
	v_fma_f32 v89, v89, v105, v101
	v_mul_f32_e32 v120, 0xbfb8aa3b, v89
	v_exp_f32_e32 v120, v120
	v_fma_f32 v88, v88, v104, v100
	v_fma_f32 v87, v87, v103, v99
	v_fma_f32 v86, v86, v102, v98
	v_add_f32_e32 v120, 1.0, v120
	v_rcp_f32_e32 v120, v120
	v_fma_f32 v84, v84, v96, v92
	v_fma_f32 v83, v83, v95, v91
	v_fma_f32 v82, v82, v94, v90
	v_mul_f32_e32 v89, v89, v120
	v_mul_f32_e32 v120, 0xbfb8aa3b, v88
	v_exp_f32_e32 v120, v120
	v_mul_f32_e32 v89, v89, v150
	v_add_f32_e32 v120, 1.0, v120
	v_rcp_f32_e32 v120, v120
	s_nop 0
	v_mul_f32_e32 v88, v88, v120
	v_mul_f32_e32 v120, 0xbfb8aa3b, v87
	v_exp_f32_e32 v120, v120
	v_mul_f32_e32 v81, v88, v81
	v_and_b32_e32 v88, 0xffff0000, v80
	v_lshlrev_b32_e32 v80, 16, v80
	v_add_f32_e32 v120, 1.0, v120
	v_rcp_f32_e32 v120, v120
	s_nop 0
	v_mul_f32_e32 v87, v87, v120
	v_mul_f32_e32 v87, v87, v88
	v_mul_f32_e32 v88, 0xbfb8aa3b, v86
	v_exp_f32_e32 v88, v88
	s_nop 0
	v_add_f32_e32 v88, 1.0, v88
	v_rcp_f32_e32 v88, v88
	s_nop 0
	v_mul_f32_e32 v86, v86, v88
	v_mul_f32_e32 v88, 0xbfb8aa3b, v85
	v_exp_f32_e32 v88, v88
	v_mul_f32_e32 v80, v86, v80
	v_and_b32_e32 v86, 0xffff0000, v79
	v_lshlrev_b32_e32 v79, 16, v79
	v_add_f32_e32 v88, 1.0, v88
	v_rcp_f32_e32 v88, v88
	s_nop 0
	v_mul_f32_e32 v85, v85, v88
	v_mul_f32_e32 v85, v85, v86
	v_mul_f32_e32 v86, 0xbfb8aa3b, v84
	v_exp_f32_e32 v86, v86
	s_nop 0
	v_add_f32_e32 v86, 1.0, v86
	v_rcp_f32_e32 v86, v86
	s_nop 0
	v_mul_f32_e32 v84, v84, v86
	v_mul_f32_e32 v86, 0xbfb8aa3b, v83
	v_exp_f32_e32 v86, v86
	v_mul_f32_e32 v79, v84, v79
	v_and_b32_e32 v84, 0xffff0000, v78
	v_lshlrev_b32_e32 v78, 16, v78
	v_add_f32_e32 v86, 1.0, v86
	v_rcp_f32_e32 v86, v86
	s_nop 0
	v_mul_f32_e32 v83, v83, v86
	v_mul_f32_e32 v83, v83, v84
	v_mul_f32_e32 v84, 0xbfb8aa3b, v82
	v_exp_f32_e32 v84, v84
	s_nop 0
	v_add_f32_e32 v84, 1.0, v84
	v_rcp_f32_e32 v84, v84
	s_nop 0
	v_mul_f32_e32 v82, v82, v84
	v_mul_f32_e32 v78, v82, v78
	v_cvt_pk_bf16_f32 v78, v78, v83
	v_cvt_pk_bf16_f32 v79, v79, v85
	v_cvt_pk_bf16_f32 v80, v80, v87
	v_cvt_pk_bf16_f32 v81, v81, v89
	buffer_store_dwordx4 v[78:81], v148, s[8:11], 0 offen sc1
	s_waitcnt lgkmcnt(4)
	s_nop 0
	v_pk_add_f32 v[78:79], v[114:115], v[116:117]
	v_and_b32_e32 v80, 0xffff0000, v77
	v_pk_mul_f32 v[78:79], v[78:79], s[2:3] op_sel_hi:[1,0]
	v_lshlrev_b32_e32 v77, 16, v77
	v_fma_f32 v78, -v79, v79, v78
	v_max_f32_e32 v78, 0, v78
	v_add_f32_e32 v78, 0x358637bd, v78
	v_cmp_gt_f32_e32 vcc, s33, v78
	v_mul_f32_e32 v81, 0x4b800000, v78
	s_nop 0
	v_cndmask_b32_e32 v78, v78, v81, vcc
	v_rsq_f32_e32 v78, v78
	s_nop 0
	v_mul_f32_e32 v81, 0x45800000, v78
	v_cndmask_b32_e32 v78, v78, v81, vcc
	v_mul_f32_e64 v249, -v79, v78
	v_fma_f32 v81, v147, v78, v249
	v_fma_f32 v81, v81, v105, v101
	v_mul_f32_e32 v82, 0xbfb8aa3b, v81
	v_exp_f32_e32 v82, v82
	s_nop 0
	v_add_f32_e32 v82, 1.0, v82
	v_rcp_f32_e32 v82, v82
	s_nop 0
	v_mul_f32_e32 v81, v81, v82
	v_mul_f32_e32 v80, v81, v80
	v_fma_f32 v81, v146, v78, v249
	v_fma_f32 v81, v81, v104, v100
	v_mul_f32_e32 v82, 0xbfb8aa3b, v81
	v_exp_f32_e32 v82, v82
	s_nop 0
	v_add_f32_e32 v82, 1.0, v82
	v_rcp_f32_e32 v82, v82
	s_nop 0
	v_mul_f32_e32 v81, v81, v82
	v_fma_f32 v82, v145, v78, v249
	v_fma_f32 v82, v82, v103, v99
	v_mul_f32_e32 v83, 0xbfb8aa3b, v82
	v_exp_f32_e32 v83, v83
	v_mul_f32_e32 v77, v81, v77
	v_and_b32_e32 v81, 0xffff0000, v76
	v_lshlrev_b32_e32 v76, 16, v76
	v_add_f32_e32 v83, 1.0, v83
	v_rcp_f32_e32 v83, v83
	s_nop 0
	v_mul_f32_e32 v82, v82, v83
	v_mul_f32_e32 v81, v82, v81
	v_fma_f32 v82, v144, v78, v249
	v_fma_f32 v82, v82, v102, v98
	v_mul_f32_e32 v83, 0xbfb8aa3b, v82
	v_exp_f32_e32 v83, v83
	s_nop 0
	v_add_f32_e32 v83, 1.0, v83
	v_rcp_f32_e32 v83, v83
	s_nop 0
	v_mul_f32_e32 v82, v82, v83
	v_fma_f32 v83, v143, v78, v249
	v_fma_f32 v83, v83, v97, v93
	v_mul_f32_e32 v84, 0xbfb8aa3b, v83
	v_exp_f32_e32 v84, v84
	v_mul_f32_e32 v76, v82, v76
	v_and_b32_e32 v82, 0xffff0000, v75
	v_lshlrev_b32_e32 v75, 16, v75
	v_add_f32_e32 v84, 1.0, v84
	v_rcp_f32_e32 v84, v84
	s_nop 0
	v_mul_f32_e32 v83, v83, v84
	v_mul_f32_e32 v82, v83, v82
	v_fma_f32 v83, v142, v78, v249
	v_fma_f32 v83, v83, v96, v92
	v_mul_f32_e32 v84, 0xbfb8aa3b, v83
	v_exp_f32_e32 v84, v84
	s_nop 0
	v_add_f32_e32 v84, 1.0, v84
	v_rcp_f32_e32 v84, v84
	s_nop 0
	v_mul_f32_e32 v83, v83, v84
	v_fma_f32 v84, v141, v78, v249
	v_fma_f32 v78, v140, v78, v249
	v_fma_f32 v78, v78, v94, v90
	v_fma_f32 v84, v84, v95, v91
	v_mul_f32_e32 v79, 0xbfb8aa3b, v78
	v_mul_f32_e32 v85, 0xbfb8aa3b, v84
	v_exp_f32_e32 v79, v79
	v_exp_f32_e32 v85, v85
	v_mul_f32_e32 v75, v83, v75
	v_and_b32_e32 v83, 0xffff0000, v74
	v_add_f32_e32 v79, 1.0, v79
	v_add_f32_e32 v85, 1.0, v85
	v_rcp_f32_e32 v79, v79
	v_rcp_f32_e32 v85, v85
	v_lshlrev_b32_e32 v74, 16, v74
	v_mul_f32_e32 v78, v78, v79
	v_mul_f32_e32 v84, v84, v85
	v_mul_f32_e32 v74, v78, v74
	v_mul_f32_e32 v83, v84, v83
	v_cvt_pk_bf16_f32 v74, v74, v83
	v_cvt_pk_bf16_f32 v75, v75, v82
	v_cvt_pk_bf16_f32 v76, v76, v81
	v_cvt_pk_bf16_f32 v77, v77, v80
	buffer_store_dwordx4 v[74:77], v148, s[8:11], 0 offen offset:2048 sc1
	s_waitcnt lgkmcnt(2)
	s_nop 0
	v_pk_add_f32 v[74:75], v[110:111], v[112:113]
	v_and_b32_e32 v76, 0xffff0000, v73
	v_pk_mul_f32 v[74:75], v[74:75], s[2:3] op_sel_hi:[1,0]
	v_lshlrev_b32_e32 v73, 16, v73
	v_fma_f32 v74, -v75, v75, v74
	v_max_f32_e32 v74, 0, v74
	v_add_f32_e32 v74, 0x358637bd, v74
	v_cmp_gt_f32_e32 vcc, s33, v74
	v_mul_f32_e32 v77, 0x4b800000, v74
	s_nop 0
	v_cndmask_b32_e32 v74, v74, v77, vcc
	v_rsq_f32_e32 v74, v74
	s_nop 0
	v_mul_f32_e32 v77, 0x45800000, v74
	v_cndmask_b32_e32 v74, v74, v77, vcc
	v_mul_f32_e64 v250, -v75, v74
	v_fma_f32 v77, v139, v74, v250
	v_fma_f32 v77, v77, v105, v101
	v_mul_f32_e32 v78, 0xbfb8aa3b, v77
	v_exp_f32_e32 v78, v78
	s_nop 0
	v_add_f32_e32 v78, 1.0, v78
	v_rcp_f32_e32 v78, v78
	s_nop 0
	v_mul_f32_e32 v77, v77, v78
	v_mul_f32_e32 v76, v77, v76
	v_fma_f32 v77, v138, v74, v250
	v_fma_f32 v77, v77, v104, v100
	v_mul_f32_e32 v78, 0xbfb8aa3b, v77
	v_exp_f32_e32 v78, v78
	s_nop 0
	v_add_f32_e32 v78, 1.0, v78
	v_rcp_f32_e32 v78, v78
	s_nop 0
	v_mul_f32_e32 v77, v77, v78
	v_fma_f32 v78, v137, v74, v250
	v_fma_f32 v78, v78, v103, v99
	v_mul_f32_e32 v79, 0xbfb8aa3b, v78
	v_exp_f32_e32 v79, v79
	v_mul_f32_e32 v73, v77, v73
	v_and_b32_e32 v77, 0xffff0000, v72
	v_lshlrev_b32_e32 v72, 16, v72
	v_add_f32_e32 v79, 1.0, v79
	v_rcp_f32_e32 v79, v79
	s_nop 0
	v_mul_f32_e32 v78, v78, v79
	v_mul_f32_e32 v77, v78, v77
	v_fma_f32 v78, v136, v74, v250
	v_fma_f32 v78, v78, v102, v98
	v_mul_f32_e32 v79, 0xbfb8aa3b, v78
	v_exp_f32_e32 v79, v79
	s_nop 0
	v_add_f32_e32 v79, 1.0, v79
	v_rcp_f32_e32 v79, v79
	s_nop 0
	v_mul_f32_e32 v78, v78, v79
	v_fma_f32 v79, v135, v74, v250
	v_fma_f32 v79, v79, v97, v93
	v_mul_f32_e32 v80, 0xbfb8aa3b, v79
	v_exp_f32_e32 v80, v80
	v_mul_f32_e32 v72, v78, v72
	v_and_b32_e32 v78, 0xffff0000, v71
	v_lshlrev_b32_e32 v71, 16, v71
	v_add_f32_e32 v80, 1.0, v80
	v_rcp_f32_e32 v80, v80
	s_nop 0
	v_mul_f32_e32 v79, v79, v80
	v_mul_f32_e32 v78, v79, v78
	v_fma_f32 v79, v134, v74, v250
	v_fma_f32 v79, v79, v96, v92
	v_mul_f32_e32 v80, 0xbfb8aa3b, v79
	v_exp_f32_e32 v80, v80
	s_nop 0
	v_add_f32_e32 v80, 1.0, v80
	v_rcp_f32_e32 v80, v80
	s_nop 0
	v_mul_f32_e32 v79, v79, v80
	v_fma_f32 v80, v133, v74, v250
	v_fma_f32 v74, v132, v74, v250
	v_fma_f32 v74, v74, v94, v90
	v_fma_f32 v80, v80, v95, v91
	v_mul_f32_e32 v75, 0xbfb8aa3b, v74
	v_mul_f32_e32 v81, 0xbfb8aa3b, v80
	v_exp_f32_e32 v75, v75
	v_exp_f32_e32 v81, v81
	v_mul_f32_e32 v71, v79, v71
	v_and_b32_e32 v79, 0xffff0000, v70
	v_add_f32_e32 v75, 1.0, v75
	v_add_f32_e32 v81, 1.0, v81
	v_rcp_f32_e32 v75, v75
	v_rcp_f32_e32 v81, v81
	v_lshlrev_b32_e32 v70, 16, v70
	v_mul_f32_e32 v74, v74, v75
	v_mul_f32_e32 v80, v80, v81
	v_mul_f32_e32 v70, v74, v70
	v_mul_f32_e32 v79, v80, v79
	v_cvt_pk_bf16_f32 v70, v70, v79
	v_cvt_pk_bf16_f32 v71, v71, v78
	v_cvt_pk_bf16_f32 v72, v72, v77
	v_cvt_pk_bf16_f32 v73, v73, v76
	buffer_store_dwordx4 v[70:73], v123, s[8:11], 0 offen sc1
	s_waitcnt lgkmcnt(0)
	s_nop 0
	v_pk_add_f32 v[70:71], v[106:107], v[108:109]
	v_and_b32_e32 v72, 0xffff0000, v61
	v_pk_mul_f32 v[70:71], v[70:71], s[2:3] op_sel_hi:[1,0]
	v_lshlrev_b32_e32 v61, 16, v61
	v_fma_f32 v70, -v71, v71, v70
	v_max_f32_e32 v70, 0, v70
	v_add_f32_e32 v70, 0x358637bd, v70
	v_cmp_gt_f32_e32 vcc, s33, v70
	v_mul_f32_e32 v73, 0x4b800000, v70
	s_nop 0
	v_cndmask_b32_e32 v70, v70, v73, vcc
	v_rsq_f32_e32 v70, v70
	s_nop 0
	v_mul_f32_e32 v73, 0x45800000, v70
	v_cndmask_b32_e32 v70, v70, v73, vcc
	v_mul_f32_e64 v251, -v71, v70
	v_fma_f32 v73, v131, v70, v251
	v_fma_f32 v73, v73, v105, v101
	v_mul_f32_e32 v74, 0xbfb8aa3b, v73
	v_exp_f32_e32 v74, v74
	s_nop 0
	v_add_f32_e32 v74, 1.0, v74
	v_rcp_f32_e32 v74, v74
	s_nop 0
	v_mul_f32_e32 v73, v73, v74
	v_mul_f32_e32 v72, v73, v72
	v_fma_f32 v73, v130, v70, v251
	v_fma_f32 v73, v73, v104, v100
	v_mul_f32_e32 v74, 0xbfb8aa3b, v73
	v_exp_f32_e32 v74, v74
	s_nop 0
	v_add_f32_e32 v74, 1.0, v74
	v_rcp_f32_e32 v74, v74
	s_nop 0
	v_mul_f32_e32 v73, v73, v74
	v_fma_f32 v74, v129, v70, v251
	v_fma_f32 v74, v74, v103, v99
	v_mul_f32_e32 v75, 0xbfb8aa3b, v74
	v_exp_f32_e32 v75, v75
	v_mul_f32_e32 v61, v73, v61
	v_and_b32_e32 v73, 0xffff0000, v60
	v_lshlrev_b32_e32 v60, 16, v60
	v_add_f32_e32 v75, 1.0, v75
	v_rcp_f32_e32 v75, v75
	s_nop 0
	v_mul_f32_e32 v74, v74, v75
	v_mul_f32_e32 v73, v74, v73
	v_fma_f32 v74, v128, v70, v251
	v_fmac_f32_e32 v98, v74, v102
	v_fma_f32 v75, v127, v70, v251
	v_mul_f32_e32 v74, 0xbfb8aa3b, v98
	v_fma_f32 v75, v75, v97, v93
	v_exp_f32_e32 v74, v74
	v_mul_f32_e32 v76, 0xbfb8aa3b, v75
	v_exp_f32_e32 v76, v76
	v_add_f32_e32 v74, 1.0, v74
	v_rcp_f32_e32 v74, v74
	v_add_f32_e32 v76, 1.0, v76
	v_rcp_f32_e32 v76, v76
	v_mul_f32_e32 v74, v98, v74
	v_mul_f32_e32 v60, v74, v60
	v_and_b32_e32 v74, 0xffff0000, v59
	v_mul_f32_e32 v75, v75, v76
	v_mul_f32_e32 v74, v75, v74
	v_fma_f32 v75, v126, v70, v251
	v_fma_f32 v75, v75, v96, v92
	v_mul_f32_e32 v76, 0xbfb8aa3b, v75
	v_exp_f32_e32 v76, v76
	v_lshlrev_b32_e32 v59, 16, v59
	v_add_f32_e32 v76, 1.0, v76
	v_rcp_f32_e32 v76, v76
	s_nop 0
	v_mul_f32_e32 v75, v75, v76
	v_fma_f32 v76, v125, v70, v251
	v_fma_f32 v70, v124, v70, v251
	v_fmac_f32_e32 v90, v70, v94
	v_fma_f32 v76, v76, v95, v91
	v_mul_f32_e32 v70, 0xbfb8aa3b, v90
	v_mul_f32_e32 v77, 0xbfb8aa3b, v76
	v_exp_f32_e32 v70, v70
	v_exp_f32_e32 v77, v77
	v_mul_f32_e32 v59, v75, v59
	v_and_b32_e32 v75, 0xffff0000, v58
	v_add_f32_e32 v70, 1.0, v70
	v_add_f32_e32 v77, 1.0, v77
	v_rcp_f32_e32 v70, v70
	v_rcp_f32_e32 v77, v77
	v_lshlrev_b32_e32 v58, 16, v58
	v_mul_f32_e32 v70, v90, v70
	v_mul_f32_e32 v76, v76, v77
	v_mul_f32_e32 v58, v70, v58
	v_mul_f32_e32 v75, v76, v75
	v_cvt_pk_bf16_f32 v58, v58, v75
	v_cvt_pk_bf16_f32 v59, v59, v74
	v_cvt_pk_bf16_f32 v60, v60, v73
	v_cvt_pk_bf16_f32 v61, v61, v72
	buffer_store_dwordx4 v[58:61], v123, s[8:11], 0 offen offset:2048 sc1
